# MIXA rebalance v2: third conv jobs only on CUs without a state job; two-tile and sample CUs keep one regular job per pair
# speedup vs baseline: 1.0020x; 1.0005x over previous
; #define LAS __attribute__((address_space(3)))
; __device__ __forceinline__ void mix_a_wave_jobs(Frame& F, int l) {
;     const int lane = F.lane, wave = F.wave, gi = wave & 3, c0 = 128 * gi + 2 * lane;
;     const bf16_t* U = (const bf16_t*)(F.ws + WS_U); bf16_t* YAB = (bf16_t*)(F.ws + WS_YAB);
;     const float* cw = F.in[I_CAW] + (size_t)l * 31 * DA;
;     f32x2 w[31];
; #pragma unroll
;     for (int k = 0; k < 31; ++k) w[k] = *(const f32x2*)(cw + k * DA + c0);
;     const f32x2 cbv = *(const f32x2*)(F.in[I_CAB] + l * DA + c0), lgv = *(const f32x2*)(F.in[I_LNG] + l * DA + c0), lbv = *(const f32x2*)(F.in[I_LNB] + l * DA + c0);
;     LAS f32x2* red = (LAS f32x2*)(F.lds + LDS_ARED + wave * 128);
;     for (int tb = 511 - ((int)blockIdx.x * 2 + (wave >> 2)); tb < 1096; tb += 512) {
.LBB0_267:
	v_readlane_b32 s2, v253, 12
	v_readlane_b32 s3, v253, 13
	s_waitcnt vmcnt(3)
	v_mov_b32_e32 v0, v170
	s_andn2_b64 vcc, exec, s[2:3]
	s_cbranch_vccnz .LBB0_278
	s_load_dwordx8 s[8:15], s[0:1], 0x60
	s_waitcnt vmcnt(2)
	v_lshlrev_b32_e32 v1, 1, v0
	v_readlane_b32 s16, v254, 59
	v_and_b32_e32 v75, 0x7e, v1
	v_readlane_b32 s2, v253, 9
	v_readlane_b32 s17, v254, 60
	s_mul_hi_u32 s3, s16, 0xf800
	v_or_b32_e32 v74, s2, v75
	s_mul_i32 s2, s17, 0xf800
	s_add_i32 s3, s3, s2
	s_mul_i32 s2, s16, 0xf800
	s_waitcnt lgkmcnt(0)
	s_add_u32 s2, s8, s2
	s_addc_u32 s3, s9, s3
	v_lshlrev_b32_e32 v128, 2, v74
	v_lshl_add_u64 v[62:63], s[2:3], 0, v[128:129]
	v_add_co_u32_e32 v8, vcc, s85, v62
	global_load_dwordx2 v[2:3], v128, s[2:3]
	global_load_dwordx2 v[4:5], v128, s[2:3] offset:2048
	v_addc_co_u32_e32 v9, vcc, 0, v63, vcc
	s_movk_i32 s2, 0x2000
	v_add_co_u32_e32 v12, vcc, s2, v62
	s_movk_i32 s2, 0x3000
	s_nop 0
	v_addc_co_u32_e32 v13, vcc, 0, v63, vcc
	v_add_co_u32_e32 v16, vcc, s2, v62
	s_movk_i32 s2, 0x4000
	s_nop 0
	v_addc_co_u32_e32 v17, vcc, 0, v63, vcc
	v_add_co_u32_e32 v20, vcc, s2, v62
	s_movk_i32 s2, 0x5000
	s_nop 0
	v_addc_co_u32_e32 v21, vcc, 0, v63, vcc
	v_add_co_u32_e32 v24, vcc, s2, v62
	s_movk_i32 s2, 0x6000
	s_nop 0
	v_addc_co_u32_e32 v25, vcc, 0, v63, vcc
	v_add_co_u32_e32 v28, vcc, s2, v62
	s_movk_i32 s2, 0x7000
	s_nop 0
	v_addc_co_u32_e32 v29, vcc, 0, v63, vcc
	v_add_co_u32_e32 v32, vcc, s2, v62
	s_mov_b32 s2, 0x8000
	s_nop 0
	v_addc_co_u32_e32 v33, vcc, 0, v63, vcc
	v_add_co_u32_e32 v36, vcc, s2, v62
	s_mov_b32 s2, 0x9000
	s_nop 0
	v_addc_co_u32_e32 v37, vcc, 0, v63, vcc
	v_add_co_u32_e32 v40, vcc, s2, v62
	s_mov_b32 s2, 0xa000
	s_nop 0
	v_addc_co_u32_e32 v41, vcc, 0, v63, vcc
	v_add_co_u32_e32 v44, vcc, s2, v62
	s_mov_b32 s2, 0xb000
	s_nop 0
	v_addc_co_u32_e32 v45, vcc, 0, v63, vcc
	v_add_co_u32_e32 v48, vcc, s2, v62
	s_mov_b32 s2, 0xc000
	s_nop 0
	v_addc_co_u32_e32 v49, vcc, 0, v63, vcc
	v_add_co_u32_e32 v52, vcc, s2, v62
	s_mov_b32 s2, 0xd000
	s_nop 0
	v_addc_co_u32_e32 v53, vcc, 0, v63, vcc
	v_add_co_u32_e32 v56, vcc, s2, v62
	s_mov_b32 s2, 0xe000
	s_nop 0
	v_addc_co_u32_e32 v57, vcc, 0, v63, vcc
	v_add_co_u32_e32 v60, vcc, s2, v62
	s_mov_b32 s2, 0xf000
	s_nop 0
	v_addc_co_u32_e32 v61, vcc, 0, v63, vcc
	s_ashr_i32 s37, s36, 31
	v_add_co_u32_e32 v62, vcc, s2, v62
	s_lshl_b64 s[2:3], s[36:37], 2
	s_add_u32 s6, s10, s2
	s_addc_u32 s7, s11, s3
	global_load_dwordx2 v[6:7], v[12:13], off offset:-4096
	s_nop 0
	global_load_dwordx2 v[8:9], v[8:9], off offset:2048
	s_nop 0
	global_load_dwordx2 v[10:11], v[12:13], off
	s_nop 0
	global_load_dwordx2 v[12:13], v[12:13], off offset:2048
	s_nop 0
	global_load_dwordx2 v[14:15], v[20:21], off offset:-4096
	s_nop 0
	global_load_dwordx2 v[16:17], v[16:17], off offset:2048
	s_nop 0
	global_load_dwordx2 v[18:19], v[20:21], off
	s_nop 0
	global_load_dwordx2 v[20:21], v[20:21], off offset:2048
	s_nop 0
	global_load_dwordx2 v[22:23], v[28:29], off offset:-4096
	s_nop 0
	global_load_dwordx2 v[24:25], v[24:25], off offset:2048
	s_nop 0
	global_load_dwordx2 v[26:27], v[28:29], off
	s_nop 0
	global_load_dwordx2 v[28:29], v[28:29], off offset:2048
	s_nop 0
	global_load_dwordx2 v[30:31], v[36:37], off offset:-4096
	s_nop 0
	global_load_dwordx2 v[32:33], v[32:33], off offset:2048
	s_nop 0
	global_load_dwordx2 v[34:35], v[36:37], off
	s_nop 0
	global_load_dwordx2 v[36:37], v[36:37], off offset:2048
	s_nop 0
	global_load_dwordx2 v[38:39], v[44:45], off offset:-4096
	s_nop 0
	global_load_dwordx2 v[40:41], v[40:41], off offset:2048
	s_nop 0
	global_load_dwordx2 v[42:43], v[44:45], off
	s_nop 0
	global_load_dwordx2 v[44:45], v[44:45], off offset:2048
	s_nop 0
	global_load_dwordx2 v[46:47], v[52:53], off offset:-4096
	s_nop 0
	global_load_dwordx2 v[48:49], v[48:49], off offset:2048
	s_nop 0
	global_load_dwordx2 v[50:51], v[52:53], off
	s_nop 0
	global_load_dwordx2 v[52:53], v[52:53], off offset:2048
	s_nop 0
	global_load_dwordx2 v[54:55], v[60:61], off offset:-4096
	s_nop 0
	global_load_dwordx2 v[56:57], v[56:57], off offset:2048
	s_nop 0
	global_load_dwordx2 v[58:59], v[60:61], off
	s_nop 0
	global_load_dwordx2 v[60:61], v[60:61], off offset:2048
	v_addc_co_u32_e32 v63, vcc, 0, v63, vcc
	global_load_dwordx2 v[64:65], v128, s[6:7]
	s_add_u32 s6, s12, s2
	s_addc_u32 s7, s13, s3
	s_add_u32 s2, s14, s2
	s_addc_u32 s3, s15, s3
	global_load_dwordx2 v[62:63], v[62:63], off
	v_and_b32_e32 v1, 32, v0
	global_load_dwordx2 v[66:67], v128, s[6:7]
	global_load_dwordx2 v[68:69], v128, s[2:3]
	v_cmp_eq_u32_e64 s[6:7], 0, v1
	v_xor_b32_e32 v1, 32, v196
	v_add_u32_e32 v76, 64, v197
	v_and_b32_e32 v77, 16, v0
	v_cmp_lt_i32_e32 vcc, v1, v76
	v_cmp_eq_u32_e64 s[8:9], 0, v77
	v_xor_b32_e32 v77, 16, v196
	v_cndmask_b32_e32 v1, v196, v1, vcc
	v_cmp_lt_i32_e32 vcc, v77, v76
	s_mul_i32 s2, s17, 0x780000
	s_mul_hi_u32 s3, s16, 0x780000
	v_cndmask_b32_e32 v77, v196, v77, vcc
	v_lshlrev_b32_e32 v110, 2, v77
	v_and_b32_e32 v77, 8, v0
	v_cmp_eq_u32_e64 s[10:11], 0, v77
	v_xor_b32_e32 v77, 8, v196
	v_cmp_lt_i32_e32 vcc, v77, v76
	v_lshlrev_b32_e32 v128, 1, v74
	s_add_i32 s20, s3, s2
	v_cndmask_b32_e32 v77, v196, v77, vcc
	v_lshlrev_b32_e32 v111, 2, v77
	v_and_b32_e32 v77, 4, v0
	v_cmp_eq_u32_e64 s[12:13], 0, v77
	v_xor_b32_e32 v77, 4, v196
	v_cmp_lt_i32_e32 vcc, v77, v76
	v_lshl_add_u64 v[72:73], s[74:75], 0, v[128:129]
	s_mov_b64 s[2:3], 0x9280000
	v_cndmask_b32_e32 v77, v196, v77, vcc
	v_lshlrev_b32_e32 v112, 2, v77
	v_xor_b32_e32 v77, 2, v196
	v_cmp_lt_i32_e32 vcc, v77, v76
	v_lshl_add_u64 v[70:71], v[72:73], 0, s[2:3]
	s_mov_b64 s[2:3], 0xc640000
	v_cndmask_b32_e32 v77, v196, v77, vcc
	v_lshlrev_b32_e32 v113, 2, v77
	v_xor_b32_e32 v77, 1, v196
	v_cmp_lt_i32_e32 vcc, v77, v76
	v_lshl_add_u64 v[72:73], v[72:73], 0, s[2:3]
	v_readlane_b32 s2, v254, 14
	v_cndmask_b32_e32 v76, v196, v77, vcc
	v_lshlrev_b32_e32 v114, 2, v76
	v_and_b32_e32 v76, 3, v0
	v_lshlrev_b32_e32 v1, 2, v1
	v_cmp_eq_u32_e64 s[14:15], 0, v76
	v_add_u32_e32 v115, s62, v75
	v_lshlrev_b32_e32 v128, 2, v74
	s_mov_b32 s16, s2
	v_readlane_b32 s21, v254, 13
	v_readlane_b32 s22, v253, 11
	s_sub_i32 s101, 0x1ff, s22
	s_lshl_b32 s101, s101, 2
	s_branch .LBB0_270
; __device__ __forceinline__ unsigned pk2(float lo, float hi) { unsigned r; asm("v_cvt_pk_bf16_f32 %0, %1, %2" : "=v"(r) : "v"(lo), "v"(hi)); return r; }
; __device__ __forceinline__ float silu_f(float x) { return x * sigmoid_f(x); }
; __device__ __forceinline__ void mix_a_wave_jobs(Frame& F, int l) {
;     ...
; #pragma unroll
;         for (int t = 0; t < 16; ++t) {
;             const f32x2 st_ = red[t];
;             const float mean = st_.x * (1.0f / 128.0f), var = st_.y * (1.0f / 128.0f) - mean * mean;
;             const float rstd = __builtin_amdgcn_rsqf(fmaxf(var, 0.f) + EPS);
;             const f32x2 y = (a[t] - mean) * rstd * lgv + lbv;
;             *(unsigned*)(YAB + (size_t)(rowbase + t) * D + c0) = pk2(silu_f(y.x), silu_f(y.y));
;         }
.LBB0_269:
	s_or_b64 exec, exec, s[2:3]
	s_waitcnt lgkmcnt(0)
	v_mov_b32_e32 v131, s62
	s_waitcnt lgkmcnt(0)
	ds_read2_b64 v[106:109], v131 offset1:1
	ds_read2_b64 v[116:119], v131 offset0:2 offset1:3
	ds_read2_b64 v[120:123], v131 offset0:4 offset1:5
	ds_read2_b64 v[124:127], v131 offset0:6 offset1:7
	s_brev_b32 s24, 60
	s_waitcnt lgkmcnt(3)
	v_pk_mul_f32 v[106:107], v[106:107], s[24:25] op_sel_hi:[1,0]
	v_pk_mul_f32 v[108:109], v[108:109], s[24:25] op_sel_hi:[1,0]
	v_fma_f32 v130, -v106, v106, v107
	v_max_f32_e32 v130, 0, v130
	v_add_f32_e32 v130, 0x358637bd, v130
	v_rsq_f32_e32 v130, v130
	v_pk_add_f32 v[74:75], v[74:75], v[106:107] op_sel_hi:[1,0] neg_lo:[0,1] neg_hi:[0,1]
	v_fma_f32 v106, -v108, v108, v109
	v_max_f32_e32 v106, 0, v106
	v_pk_mul_f32 v[74:75], v[74:75], v[130:131] op_sel_hi:[1,0]
	v_add_f32_e32 v106, 0x358637bd, v106
	v_pk_fma_f32 v[74:75], v[66:67], v[74:75], v[68:69]
	v_pk_add_f32 v[76:77], v[76:77], v[108:109] op_sel_hi:[1,0] neg_lo:[0,1] neg_hi:[0,1]
	v_mul_f32_e32 v107, 0xbfb8aa3b, v74
	v_exp_f32_e32 v107, v107
	v_mul_f32_e32 v130, 0xbfb8aa3b, v75
	v_exp_f32_e32 v130, v130
	s_ashr_i32 s19, s18, 31
	v_add_f32_e32 v107, 1.0, v107
	v_rcp_f32_e32 v107, v107
	v_add_f32_e32 v130, 1.0, v130
	v_rcp_f32_e32 v130, v130
	s_lshl_b64 s[2:3], s[18:19], 11
	v_mul_f32_e32 v107, v74, v107
	v_rsq_f32_e32 v74, v106
	v_mul_f32_e32 v75, v75, v130
	v_cvt_pk_bf16_f32 v130, v107, v75
	v_pk_mul_f32 v[74:75], v[76:77], v[74:75] op_sel_hi:[1,0]
	v_pk_fma_f32 v[76:77], v[66:67], v[74:75], v[68:69]
	s_nop 0
	v_mul_f32_e32 v74, 0xbfb8aa3b, v76
	v_exp_f32_e32 v106, v74
	v_lshl_add_u64 v[74:75], v[72:73], 0, s[2:3]
	s_movk_i32 s2, 0x2000
	global_store_dword v[74:75], v130, off
	v_add_f32_e32 v106, 1.0, v106
	v_rcp_f32_e32 v109, v106
	v_mul_f32_e32 v106, 0xbfb8aa3b, v77
	v_exp_f32_e32 v132, v106
	s_waitcnt lgkmcnt(2)
	v_pk_mul_f32 v[106:107], v[116:117], s[24:25] op_sel_hi:[1,0]
	v_mul_f32_e32 v76, v76, v109
	v_fma_f32 v108, -v106, v106, v107
	v_max_f32_e32 v108, 0, v108
	v_add_f32_e32 v108, 0x358637bd, v108
	v_rsq_f32_e32 v108, v108
	v_pk_add_f32 v[78:79], v[78:79], v[106:107] op_sel_hi:[1,0] neg_lo:[0,1] neg_hi:[0,1]
	v_add_f32_e32 v116, 1.0, v132
	v_rcp_f32_e32 v116, v116
	v_pk_mul_f32 v[78:79], v[78:79], v[108:109] op_sel_hi:[1,0]
	v_mul_f32_e32 v77, v77, v116
	v_pk_fma_f32 v[78:79], v[66:67], v[78:79], v[68:69]
	v_cvt_pk_bf16_f32 v76, v76, v77
	global_store_dword v[74:75], v76, off offset:2048
	v_mul_f32_e32 v106, 0xbfb8aa3b, v78
	v_exp_f32_e32 v106, v106
	v_mul_f32_e32 v107, 0xbfb8aa3b, v79
	v_exp_f32_e32 v107, v107
	v_add_f32_e32 v106, 1.0, v106
	v_rcp_f32_e32 v106, v106
	v_add_f32_e32 v76, 1.0, v107
	v_rcp_f32_e32 v107, v76
	v_pk_mul_f32 v[76:77], v[118:119], s[24:25] op_sel_hi:[1,0]
	v_mul_f32_e32 v106, v78, v106
	v_fma_f32 v78, -v76, v76, v77
	v_max_f32_e32 v78, 0, v78
	v_add_f32_e32 v78, 0x358637bd, v78
	v_rsq_f32_e32 v78, v78
	v_mul_f32_e32 v79, v79, v107
	v_pk_add_f32 v[76:77], v[80:81], v[76:77] op_sel_hi:[1,0] neg_lo:[0,1] neg_hi:[0,1]
	v_cvt_pk_bf16_f32 v106, v106, v79
	s_nop 0
	v_pk_mul_f32 v[76:77], v[76:77], v[78:79] op_sel_hi:[1,0]
	s_nop 0
	v_pk_fma_f32 v[76:77], v[66:67], v[76:77], v[68:69]
	s_nop 0
	v_mul_f32_e32 v78, 0xbfb8aa3b, v76
	v_exp_f32_e32 v80, v78
	v_add_co_u32_e32 v78, vcc, s85, v74
	v_add_f32_e32 v80, 1.0, v80
	v_rcp_f32_e32 v107, v80
	v_addc_co_u32_e32 v79, vcc, 0, v75, vcc
	v_add_co_u32_e32 v80, vcc, s2, v74
	v_mul_f32_e32 v108, v76, v107
	s_nop 0
	v_addc_co_u32_e32 v81, vcc, 0, v75, vcc
	global_store_dword v[80:81], v106, off offset:-4096
	v_mul_f32_e32 v76, 0xbfb8aa3b, v77
	s_waitcnt lgkmcnt(1)
	v_pk_mul_f32 v[106:107], v[120:121], s[24:25] op_sel_hi:[1,0]
	v_exp_f32_e32 v109, v76
	v_fma_f32 v76, -v106, v106, v107
	v_max_f32_e32 v76, 0, v76
	v_add_f32_e32 v76, 0x358637bd, v76
	v_rsq_f32_e32 v76, v76
	v_pk_add_f32 v[82:83], v[82:83], v[106:107] op_sel_hi:[1,0] neg_lo:[0,1] neg_hi:[0,1]
	v_add_f32_e32 v109, 1.0, v109
	v_rcp_f32_e32 v109, v109
	v_pk_mul_f32 v[82:83], v[82:83], v[76:77] op_sel_hi:[1,0]
	s_movk_i32 s2, 0x3000
	v_pk_fma_f32 v[82:83], v[66:67], v[82:83], v[68:69]
	v_mul_f32_e32 v77, v77, v109
	v_mul_f32_e32 v76, 0xbfb8aa3b, v82
	v_exp_f32_e32 v76, v76
	v_cvt_pk_bf16_f32 v77, v108, v77
	global_store_dword v[78:79], v77, off offset:2048
	v_add_f32_e32 v76, 1.0, v76
	v_rcp_f32_e32 v79, v76
	v_mul_f32_e32 v76, 0xbfb8aa3b, v83
	v_exp_f32_e32 v106, v76
	v_pk_mul_f32 v[76:77], v[122:123], s[24:25] op_sel_hi:[1,0]
	v_add_f32_e32 v106, 1.0, v106
	v_fma_f32 v78, -v76, v76, v77
	v_max_f32_e32 v78, 0, v78
	v_add_f32_e32 v78, 0x358637bd, v78
	v_rsq_f32_e32 v78, v78
	v_pk_add_f32 v[76:77], v[88:89], v[76:77] op_sel_hi:[1,0] neg_lo:[0,1] neg_hi:[0,1]
	v_rcp_f32_e32 v106, v106
	v_pk_mul_f32 v[76:77], v[76:77], v[78:79] op_sel_hi:[1,0]
	s_nop 0
	v_pk_fma_f32 v[76:77], v[66:67], v[76:77], v[68:69]
	v_mul_f32_e32 v79, v82, v79
	v_mul_f32_e32 v78, 0xbfb8aa3b, v76
	v_exp_f32_e32 v78, v78
	v_mul_f32_e32 v82, v83, v106
	v_cvt_pk_bf16_f32 v83, v79, v82
	global_store_dword v[80:81], v83, off
	v_add_f32_e32 v78, 1.0, v78
	v_rcp_f32_e32 v88, v78
	v_mul_f32_e32 v78, 0xbfb8aa3b, v77
	v_exp_f32_e32 v89, v78
	s_waitcnt lgkmcnt(0)
; __device__ __forceinline__ unsigned pk2(float lo, float hi) { unsigned r; asm("v_cvt_pk_bf16_f32 %0, %1, %2" : "=v"(r) : "v"(lo), "v"(hi)); return r; }
; __device__ __forceinline__ float silu_f(float x) { return x * sigmoid_f(x); }
; __device__ __forceinline__ void mix_a_wave_jobs(Frame& F, int l) {
;     ...
; #pragma unroll
;         for (int t = 0; t < 16; ++t) {
;             const f32x2 st_ = red[t];
;             const float mean = st_.x * (1.0f / 128.0f), var = st_.y * (1.0f / 128.0f) - mean * mean;
;             const float rstd = __builtin_amdgcn_rsqf(fmaxf(var, 0.f) + EPS);
;             const f32x2 y = (a[t] - mean) * rstd * lgv + lbv;
;             *(unsigned*)(YAB + (size_t)(rowbase + t) * D + c0) = pk2(silu_f(y.x), silu_f(y.y));
;         }
	v_pk_mul_f32 v[78:79], v[124:125], s[24:25] op_sel_hi:[1,0]
	v_mul_f32_e32 v76, v76, v88
	v_fma_f32 v82, -v78, v78, v79
	v_max_f32_e32 v82, 0, v82
	v_add_f32_e32 v82, 0x358637bd, v82
	v_rsq_f32_e32 v82, v82
	v_pk_add_f32 v[78:79], v[86:87], v[78:79] op_sel_hi:[1,0] neg_lo:[0,1] neg_hi:[0,1]
	v_add_f32_e32 v89, 1.0, v89
	v_rcp_f32_e32 v89, v89
	v_pk_mul_f32 v[78:79], v[78:79], v[82:83] op_sel_hi:[1,0]
	v_add_co_u32_e32 v86, vcc, s2, v74
	v_pk_fma_f32 v[78:79], v[66:67], v[78:79], v[68:69]
	v_mul_f32_e32 v77, v77, v89
	v_mul_f32_e32 v82, 0xbfb8aa3b, v78
	v_exp_f32_e32 v82, v82
	v_mul_f32_e32 v83, 0xbfb8aa3b, v79
	v_exp_f32_e32 v83, v83
	v_cvt_pk_bf16_f32 v76, v76, v77
	v_add_f32_e32 v82, 1.0, v82
	v_rcp_f32_e32 v82, v82
	global_store_dword v[80:81], v76, off offset:2048
	v_add_f32_e32 v76, 1.0, v83
	v_rcp_f32_e32 v81, v76
	v_pk_mul_f32 v[76:77], v[126:127], s[24:25] op_sel_hi:[1,0]
	v_mul_f32_e32 v80, v78, v82
	v_fma_f32 v78, -v76, v76, v77
	v_max_f32_e32 v78, 0, v78
	v_add_f32_e32 v78, 0x358637bd, v78
	v_rsq_f32_e32 v78, v78
	v_mul_f32_e32 v79, v79, v81
	v_pk_add_f32 v[76:77], v[84:85], v[76:77] op_sel_hi:[1,0] neg_lo:[0,1] neg_hi:[0,1]
	v_cvt_pk_bf16_f32 v79, v80, v79
	v_addc_co_u32_e32 v87, vcc, 0, v75, vcc
	v_pk_mul_f32 v[76:77], v[76:77], v[78:79] op_sel_hi:[1,0]
	s_movk_i32 s2, 0x4000
	v_pk_fma_f32 v[84:85], v[66:67], v[76:77], v[68:69]
	v_add_co_u32_e32 v88, vcc, s2, v74
	v_mul_f32_e32 v76, 0xbfb8aa3b, v84
	v_exp_f32_e32 v76, v76
	v_addc_co_u32_e32 v89, vcc, 0, v75, vcc
	global_store_dword v[88:89], v79, off offset:-4096
	v_add_f32_e32 v76, 1.0, v76
	v_rcp_f32_e32 v80, v76
	ds_read2_b64 v[76:79], v131 offset0:8 offset1:9
	s_movk_i32 s2, 0x5000
	v_mul_f32_e32 v106, v84, v80
	v_mul_f32_e32 v80, 0xbfb8aa3b, v85
	v_exp_f32_e32 v107, v80
	ds_read2_b64 v[80:83], v131 offset0:10 offset1:11
	s_waitcnt lgkmcnt(1)
	v_pk_mul_f32 v[76:77], v[76:77], s[24:25] op_sel_hi:[1,0]
	v_pk_mul_f32 v[78:79], v[78:79], s[24:25] op_sel_hi:[1,0]
	v_fma_f32 v84, -v76, v76, v77
	v_max_f32_e32 v84, 0, v84
	v_add_f32_e32 v84, 0x358637bd, v84
	v_rsq_f32_e32 v84, v84
	v_pk_add_f32 v[76:77], v[90:91], v[76:77] op_sel_hi:[1,0] neg_lo:[0,1] neg_hi:[0,1]
	v_add_f32_e32 v107, 1.0, v107
	v_rcp_f32_e32 v107, v107
	v_pk_mul_f32 v[76:77], v[76:77], v[84:85] op_sel_hi:[1,0]
	v_mul_f32_e32 v85, v85, v107
	v_pk_fma_f32 v[76:77], v[66:67], v[76:77], v[68:69]
	v_cvt_pk_bf16_f32 v85, v106, v85
	global_store_dword v[86:87], v85, off offset:2048
	v_mul_f32_e32 v84, 0xbfb8aa3b, v76
	v_exp_f32_e32 v84, v84
	v_mul_f32_e32 v86, 0xbfb8aa3b, v77
	v_exp_f32_e32 v86, v86
	v_add_f32_e32 v84, 1.0, v84
	v_rcp_f32_e32 v85, v84
	v_fma_f32 v84, -v78, v78, v79
	v_max_f32_e32 v84, 0, v84
	v_add_f32_e32 v84, 0x358637bd, v84
	v_rsq_f32_e32 v84, v84
	v_pk_add_f32 v[78:79], v[92:93], v[78:79] op_sel_hi:[1,0] neg_lo:[0,1] neg_hi:[0,1]
	v_add_f32_e32 v86, 1.0, v86
	v_rcp_f32_e32 v86, v86
	v_pk_mul_f32 v[78:79], v[78:79], v[84:85] op_sel_hi:[1,0]
	v_mul_f32_e32 v76, v76, v85
	v_pk_fma_f32 v[78:79], v[66:67], v[78:79], v[68:69]
	v_mul_f32_e32 v77, v77, v86
	v_mul_f32_e32 v84, 0xbfb8aa3b, v78
	v_exp_f32_e32 v84, v84
	v_cvt_pk_bf16_f32 v76, v76, v77
	global_store_dword v[88:89], v76, off
	v_mul_f32_e32 v76, 0xbfb8aa3b, v79
	v_add_f32_e32 v84, 1.0, v84
	v_rcp_f32_e32 v84, v84
	v_exp_f32_e32 v85, v76
	s_waitcnt lgkmcnt(0)
	v_pk_mul_f32 v[76:77], v[80:81], s[24:25] op_sel_hi:[1,0]
	v_mul_f32_e32 v84, v78, v84
	v_fma_f32 v78, -v76, v76, v77
	v_max_f32_e32 v78, 0, v78
	v_add_f32_e32 v78, 0x358637bd, v78
	v_rsq_f32_e32 v78, v78
	v_pk_add_f32 v[76:77], v[94:95], v[76:77] op_sel_hi:[1,0] neg_lo:[0,1] neg_hi:[0,1]
	v_add_f32_e32 v80, 1.0, v85
	v_rcp_f32_e32 v80, v80
	v_pk_mul_f32 v[76:77], v[76:77], v[78:79] op_sel_hi:[1,0]
	v_mul_f32_e32 v79, v79, v80
	v_pk_fma_f32 v[76:77], v[66:67], v[76:77], v[68:69]
	v_cvt_pk_bf16_f32 v79, v84, v79
	global_store_dword v[88:89], v79, off offset:2048
	v_mul_f32_e32 v78, 0xbfb8aa3b, v76
	v_mul_f32_e32 v81, 0xbfb8aa3b, v77
	v_exp_f32_e32 v78, v78
	v_exp_f32_e32 v81, v81
	v_add_co_u32_e32 v84, vcc, s2, v74
	v_add_f32_e32 v78, 1.0, v78
	v_add_f32_e32 v80, 1.0, v81
	v_rcp_f32_e32 v78, v78
	v_rcp_f32_e32 v80, v80
	v_addc_co_u32_e32 v85, vcc, 0, v75, vcc
	v_mul_f32_e32 v76, v76, v78
	v_mul_f32_e32 v77, v77, v80
	v_cvt_pk_bf16_f32 v79, v76, v77
	v_pk_mul_f32 v[76:77], v[82:83], s[24:25] op_sel_hi:[1,0]
	s_movk_i32 s2, 0x6000
	v_fma_f32 v78, -v76, v76, v77
	v_max_f32_e32 v78, 0, v78
	v_add_f32_e32 v78, 0x358637bd, v78
	v_rsq_f32_e32 v78, v78
	v_pk_add_f32 v[76:77], v[98:99], v[76:77] op_sel_hi:[1,0] neg_lo:[0,1] neg_hi:[0,1]
	v_add_co_u32_e32 v88, vcc, s2, v74
	v_pk_mul_f32 v[76:77], v[76:77], v[78:79] op_sel_hi:[1,0]
	s_nop 0
	v_addc_co_u32_e32 v89, vcc, 0, v75, vcc
	v_pk_fma_f32 v[86:87], v[66:67], v[76:77], v[68:69]
	global_store_dword v[88:89], v79, off offset:-4096
	v_mul_f32_e32 v76, 0xbfb8aa3b, v86
	v_exp_f32_e32 v76, v76
	s_movk_i32 s2, 0x7000
	v_add_co_u32_e32 v74, vcc, s2, v74
	v_add_f32_e32 v80, 1.0, v76
	ds_read2_b64 v[76:79], v131 offset0:12 offset1:13
	v_rcp_f32_e32 v91, v80
	v_mul_f32_e32 v80, 0xbfb8aa3b, v87
	v_exp_f32_e32 v92, v80
	ds_read2_b64 v[80:83], v131 offset0:14 offset1:15
	s_waitcnt lgkmcnt(1)
; __device__ __forceinline__ unsigned pk2(float lo, float hi) { unsigned r; asm("v_cvt_pk_bf16_f32 %0, %1, %2" : "=v"(r) : "v"(lo), "v"(hi)); return r; }
; __device__ __forceinline__ float silu_f(float x) { return x * sigmoid_f(x); }
; __device__ __forceinline__ void mix_a_wave_jobs(Frame& F, int l) {
;     ...
;     for (int tb = 511 - ((int)blockIdx.x * 2 + (wave >> 2)); tb < 1096; tb += 512) {
;     ...
; #pragma unroll
;         for (int t = 0; t < 16; ++t) {
;             const f32x2 st_ = red[t];
;             const float mean = st_.x * (1.0f / 128.0f), var = st_.y * (1.0f / 128.0f) - mean * mean;
;             const float rstd = __builtin_amdgcn_rsqf(fmaxf(var, 0.f) + EPS);
;             const f32x2 y = (a[t] - mean) * rstd * lgv + lbv;
;             *(unsigned*)(YAB + (size_t)(rowbase + t) * D + c0) = pk2(silu_f(y.x), silu_f(y.y));
;         }
;         asm volatile("s_waitcnt lgkmcnt(0)" ::: "memory");
;     }
	v_pk_mul_f32 v[76:77], v[76:77], s[24:25] op_sel_hi:[1,0]
	v_mul_f32_e32 v86, v86, v91
	v_fma_f32 v90, -v76, v76, v77
	v_max_f32_e32 v90, 0, v90
	v_add_f32_e32 v90, 0x358637bd, v90
	v_rsq_f32_e32 v90, v90
	v_pk_add_f32 v[76:77], v[96:97], v[76:77] op_sel_hi:[1,0] neg_lo:[0,1] neg_hi:[0,1]
	v_add_f32_e32 v92, 1.0, v92
	v_rcp_f32_e32 v92, v92
	v_pk_mul_f32 v[76:77], v[76:77], v[90:91] op_sel_hi:[1,0]
	v_pk_mul_f32 v[78:79], v[78:79], s[24:25] op_sel_hi:[1,0]
	v_pk_fma_f32 v[76:77], v[66:67], v[76:77], v[68:69]
	v_mul_f32_e32 v87, v87, v92
	v_mul_f32_e32 v90, 0xbfb8aa3b, v76
	v_exp_f32_e32 v90, v90
	v_cvt_pk_bf16_f32 v87, v86, v87
	global_store_dword v[84:85], v87, off offset:2048
	v_addc_co_u32_e32 v75, vcc, 0, v75, vcc
	v_add_f32_e32 v86, 1.0, v90
	v_rcp_f32_e32 v90, v86
	v_mul_f32_e32 v86, 0xbfb8aa3b, v77
	v_exp_f32_e32 v91, v86
	v_fma_f32 v86, -v78, v78, v79
	v_max_f32_e32 v86, 0, v86
	v_add_f32_e32 v86, 0x358637bd, v86
	v_rsq_f32_e32 v86, v86
	v_pk_add_f32 v[78:79], v[100:101], v[78:79] op_sel_hi:[1,0] neg_lo:[0,1] neg_hi:[0,1]
	v_add_f32_e32 v91, 1.0, v91
	v_rcp_f32_e32 v91, v91
	v_pk_mul_f32 v[78:79], v[78:79], v[86:87] op_sel_hi:[1,0]
	v_mul_f32_e32 v76, v76, v90
	v_pk_fma_f32 v[78:79], v[66:67], v[78:79], v[68:69]
	v_mul_f32_e32 v77, v77, v91
	v_mul_f32_e32 v86, 0xbfb8aa3b, v78
	v_exp_f32_e32 v86, v86
	v_mul_f32_e32 v85, 0xbfb8aa3b, v79
	v_exp_f32_e32 v85, v85
	v_cvt_pk_bf16_f32 v76, v76, v77
	v_add_f32_e32 v84, 1.0, v86
	v_rcp_f32_e32 v84, v84
	global_store_dword v[88:89], v76, off
	v_add_f32_e32 v76, 1.0, v85
	v_rcp_f32_e32 v85, v76
	s_waitcnt lgkmcnt(0)
	v_pk_mul_f32 v[76:77], v[80:81], s[24:25] op_sel_hi:[1,0]
	v_mul_f32_e32 v84, v78, v84
	v_fma_f32 v78, -v76, v76, v77
	v_max_f32_e32 v78, 0, v78
	v_add_f32_e32 v78, 0x358637bd, v78
	v_rsq_f32_e32 v78, v78
	v_mul_f32_e32 v79, v79, v85
	v_pk_add_f32 v[76:77], v[102:103], v[76:77] op_sel_hi:[1,0] neg_lo:[0,1] neg_hi:[0,1]
	v_cvt_pk_bf16_f32 v79, v84, v79
	global_store_dword v[88:89], v79, off offset:2048
	v_pk_mul_f32 v[76:77], v[76:77], v[78:79] op_sel_hi:[1,0]
	v_pk_fma_f32 v[76:77], v[66:67], v[76:77], v[68:69]
	v_mul_f32_e32 v78, 0xbfb8aa3b, v76
	v_exp_f32_e32 v78, v78
	v_mul_f32_e32 v80, 0xbfb8aa3b, v77
	v_exp_f32_e32 v80, v80
	v_add_f32_e32 v78, 1.0, v78
	v_rcp_f32_e32 v81, v78
	v_add_f32_e32 v78, 1.0, v80
	v_rcp_f32_e32 v84, v78
	v_pk_mul_f32 v[78:79], v[82:83], s[24:25] op_sel_hi:[1,0]
	v_mul_f32_e32 v81, v76, v81
	v_fma_f32 v80, -v78, v78, v79
	v_max_f32_e32 v80, 0, v80
	v_add_f32_e32 v80, 0x358637bd, v80
	v_rsq_f32_e32 v80, v80
	v_mul_f32_e32 v82, v77, v84
	v_pk_add_f32 v[76:77], v[104:105], v[78:79] op_sel_hi:[1,0] neg_lo:[0,1] neg_hi:[0,1]
	s_nop 0
	v_pk_mul_f32 v[76:77], v[76:77], v[80:81] op_sel_hi:[1,0]
	v_cvt_pk_bf16_f32 v80, v81, v82
	global_store_dword v[74:75], v80, off
	v_pk_fma_f32 v[76:77], v[66:67], v[76:77], v[68:69]
	s_nop 0
	v_mul_f32_e32 v78, 0xbfb8aa3b, v76
	v_exp_f32_e32 v78, v78
	v_mul_f32_e32 v79, 0xbfb8aa3b, v77
	v_exp_f32_e32 v79, v79
	v_add_f32_e32 v78, 1.0, v78
	v_rcp_f32_e32 v78, v78
	v_add_f32_e32 v79, 1.0, v79
	v_rcp_f32_e32 v79, v79
	v_mul_f32_e32 v76, v76, v78
	v_mul_f32_e32 v77, v77, v79
	v_cvt_pk_bf16_f32 v76, v76, v77
	global_store_dword v[74:75], v76, off offset:2048
	s_waitcnt lgkmcnt(0)
	s_add_i32 s101, s101, 1
	s_lshr_b32 s2, s101, 2
	s_and_b32 s3, s101, 3
	s_cmp_lt_u32 s2, 48
	s_cbranch_scc1 .LBB0_278
	s_cmpk_ge_u32 s2, 0x1b8
	s_cbranch_scc1 .Lmxa_bc
	s_cmp_eq_u32 s3, 1
	s_cbranch_scc1 .Lmxa_p512
	s_cmp_eq_u32 s3, 2
	s_cbranch_scc0 .LBB0_278
	s_sub_i32 s2, s2, 48
	s_cmpk_lt_u32 s2, 0x50
	s_cbranch_scc1 .Lmxa_k
	s_sub_i32 s2, s2, 0x110
	s_cmpk_lt_u32 s2, 0x50
	s_cbranch_scc1 .LBB0_278
.Lmxa_k:
	s_cmpk_ge_u32 s2, 0x70
	s_cbranch_scc1 .LBB0_278
	s_add_i32 s22, s2, 0x3d0
	s_cmp_lt_u32 s2, 48
	s_cbranch_scc1 .Lmxa_set
	s_add_i32 s22, s2, 0x1d8

; __device__ __forceinline__ void mix_a_wave_jobs(Frame& F, int l) {
;     ...
;     for (int tb = 511 - ((int)blockIdx.x * 2 + (wave >> 2)); tb < 1096; tb += 512) {
.Lmxa_bc:
	s_cmpk_ge_u32 s2, 0x1f8
	s_cbranch_scc1 .Lmxa_c
	s_cmp_eq_u32 s3, 1
	s_cbranch_scc0 .LBB0_278
	s_addk_i32 s22, 0x400
	s_addk_i32 s16, 0x4000
	s_addk_i32 s21, 0x800
	s_branch .LBB0_270
.Lmxa_c:
	s_cmp_ge_u32 s3, 3
	s_cbranch_scc1 .LBB0_278
